# combined: NA vccz branch + NA/MLA four row-sum accumulators + P4 G23C LDS-staged ss
# speedup vs baseline: 1.0010x; 1.0010x over previous
.Lna_wloop:
	s_sub_i32 s36, s24, s23
	s_cmp_lt_u32 s36, s63
	s_cselect_b64 s[40:41], -1, 0
	s_add_i32 s36, s36, 1
	s_cmp_lt_u32 s36, 8
	s_cselect_b64 s[44:45], -1, 0
	s_sub_i32 s37, s36, s62
	s_cmp_lt_u32 s37, 8
	s_cselect_b64 s[46:47], -1, 0
	s_and_b64 s[48:49], s[44:45], s[64:65]
	s_andn2_b64 s[38:39], s[46:47], s[64:65]
	s_or_b64 s[48:49], s[48:49], s[38:39]
	s_or_b64 s[42:43], s[44:45], s[46:47]
	s_and_b64 s[44:45], s[44:45], s[46:47]
	s_and_b64 s[44:45], s[44:45], s[40:41]
	s_cmp_eq_u64 s[44:45], 0
	s_cbranch_scc1 .Lna_slow_w1
	ds_read_b128 v[146:149], v199 offset:0
	ds_read_b128 v[150:153], v199 offset:32
	ds_read_b128 v[154:157], v199 offset:64
	ds_read_b128 v[158:161], v199 offset:96
	v_add_u32_e32 v210, s25, v208
	v_exp_f32_e32 v66, v66
	v_exp_f32_e32 v67, v67
	v_exp_f32_e32 v68, v68
	v_exp_f32_e32 v69, v69
	v_add_f32_e32 v213, v213, v66
	v_add_f32_e32 v214, v214, v67
	s_waitcnt lgkmcnt(3)
	v_mfma_f32_32x32x16_bf16 v[34:49], v[146:149], v[98:101], v[114:129]
	ds_read_b64 v[162:163], v201 offset:8704
	ds_read_b64 v[164:165], v201 offset:8720
	v_add_f32_e32 v178, v178, v68
	v_add_f32_e32 v179, v179, v69
	v_exp_f32_e32 v70, v70
	v_exp_f32_e32 v71, v71
	v_exp_f32_e32 v72, v72
	v_exp_f32_e32 v73, v73
	s_waitcnt lgkmcnt(4)
	v_mfma_f32_32x32x16_bf16 v[34:49], v[150:153], v[102:105], v[34:49]
	ds_read_b64 v[166:167], v201 offset:13056
	ds_read_b64 v[168:169], v201 offset:13072
	v_add_f32_e32 v213, v213, v70
	v_add_f32_e32 v214, v214, v71
	v_add_f32_e32 v178, v178, v72
	v_add_f32_e32 v179, v179, v73
	v_cvt_pk_bf16_f32 v66, v66, v67
	v_cvt_pk_bf16_f32 v67, v68, v69
	v_cvt_pk_bf16_f32 v68, v70, v71
	v_cvt_pk_bf16_f32 v69, v72, v73
	s_waitcnt lgkmcnt(5)
	v_mfma_f32_32x32x16_bf16 v[34:49], v[154:157], v[106:109], v[34:49]
	ds_read_b64 v[170:171], v201 offset:8736
	ds_read_b64 v[172:173], v201 offset:8752
	v_exp_f32_e32 v74, v74
	v_exp_f32_e32 v75, v75
	v_exp_f32_e32 v76, v76
	v_exp_f32_e32 v77, v77
	v_add_f32_e32 v213, v213, v74
	s_waitcnt lgkmcnt(6)
	v_mfma_f32_32x32x16_bf16 v[34:49], v[158:161], v[110:113], v[34:49]
	ds_read_b64 v[174:175], v201 offset:13088
	ds_read_b64 v[176:177], v201 offset:13104
	ds_read_b128 v[146:149], v210 offset:0
	ds_read_b128 v[150:153], v210 offset:32
	ds_read_b128 v[154:157], v210 offset:64
	ds_read_b128 v[158:161], v210 offset:96
	v_add_f32_e32 v214, v214, v75
	v_add_f32_e32 v178, v178, v76
	v_add_f32_e32 v179, v179, v77
	v_exp_f32_e32 v78, v78
	v_exp_f32_e32 v79, v79
	v_exp_f32_e32 v80, v80
	s_waitcnt lgkmcnt(10)
	v_mfma_f32_32x32x16_bf16 v[2:17], v[162:165], v[66:69], v[2:17]
	v_exp_f32_e32 v81, v81
	v_add_f32_e32 v213, v213, v78
	v_add_f32_e32 v214, v214, v79
	v_add_f32_e32 v178, v178, v80
	v_add_f32_e32 v179, v179, v81
	v_cvt_pk_bf16_f32 v74, v74, v75
	v_cvt_pk_bf16_f32 v75, v76, v77
	v_cvt_pk_bf16_f32 v76, v78, v79
	s_waitcnt lgkmcnt(8)
	v_mfma_f32_32x32x16_bf16 v[18:33], v[166:169], v[66:69], v[18:33]
	v_cvt_pk_bf16_f32 v77, v80, v81
	s_waitcnt lgkmcnt(0)
	v_add_f32_e32 v34, v34, v146
	v_add_f32_e32 v35, v35, v147
	v_add_f32_e32 v36, v36, v148
	v_add_f32_e32 v37, v37, v149
	v_add_f32_e32 v38, v38, v150
	v_add_f32_e32 v39, v39, v151
	v_add_f32_e32 v40, v40, v152
	v_add_f32_e32 v41, v41, v153
	v_mfma_f32_32x32x16_bf16 v[2:17], v[170:173], v[74:77], v[2:17]
	v_add_f32_e32 v42, v42, v154
	v_add_f32_e32 v43, v43, v155
	v_add_f32_e32 v44, v44, v156
	v_add_f32_e32 v45, v45, v157
	v_add_f32_e32 v46, v46, v158
	v_add_f32_e32 v47, v47, v159
	v_add_f32_e32 v48, v48, v160
	v_add_f32_e32 v49, v49, v161
	v_max3_f32 v216, v34, v35, v36
	v_mfma_f32_32x32x16_bf16 v[18:33], v[174:177], v[74:77], v[18:33]
	s_waitcnt vmcnt(2)
	ds_write_b128 v204, v[230:233] offset:9216
	ds_write_b64 v205, v[234:235] offset:0
	ds_write_b64 v205, v[236:237] offset:8
	global_load_dwordx4 v[230:233], v206, s[12:13]
	s_add_i32 s20, s20, 1
	s_add_u32 s12, s12, 0x2000
	s_addc_u32 s13, s13, 0
	s_cmp_eq_u32 s20, s22
	s_cselect_b32 s12, s16, s12
	s_cselect_b32 s13, s17, s13
	global_load_dwordx4 v[234:237], v207, s[14:15]
	s_add_i32 s21, s21, 1
	s_add_u32 s14, s14, 0x80
	s_addc_u32 s15, s15, 0
	s_cmp_eq_u32 s21, s22
	s_cselect_b32 s14, s18, s14
	s_cselect_b32 s15, s19, s15
	v_max3_f32 v217, v42, v43, v44
	v_max3_f32 v216, v216, v37, v38
	v_max3_f32 v217, v217, v45, v46
	v_max3_f32 v216, v216, v39, v40
	v_max3_f32 v217, v217, v47, v48
	v_max_f32_e32 v216, v216, v41
	v_max_f32_e32 v217, v217, v49
	v_max_f32_e32 v216, v216, v217
	v_cmp_lt_f32_e32 vcc, 4.0, v216
	s_or_b64 vcc, vcc, s[26:27]
	s_cbranch_vccz .Lna_nr_w1f
	v_mov_b32_e32 v217, v216
	s_nop 1
	v_permlane32_swap_b32_e32 v216, v217
	v_max_f32_e32 v215, v216, v217
	s_nop 15
	v_max_f32_e32 v216, v215, v220
	v_cmp_lt_f32_e32 vcc, 0xf0c9f2ca, v215
	s_nop 1
	v_cndmask_b32_e32 v216, 0, v216, vcc
	v_exp_f32_e64 v217, -v216
	v_add_f32_e32 v212, v212, v216
	v_and_b32_e32 v217, v217, v221
	v_sub_f32_e32 v34, v34, v216
	v_sub_f32_e32 v35, v35, v216
	v_sub_f32_e32 v36, v36, v216
	v_sub_f32_e32 v37, v37, v216
	v_sub_f32_e32 v38, v38, v216
	v_sub_f32_e32 v39, v39, v216
	v_sub_f32_e32 v40, v40, v216
	v_sub_f32_e32 v41, v41, v216
	v_sub_f32_e32 v42, v42, v216
	v_sub_f32_e32 v43, v43, v216
	v_sub_f32_e32 v44, v44, v216
	v_sub_f32_e32 v45, v45, v216
	v_sub_f32_e32 v46, v46, v216
	v_sub_f32_e32 v47, v47, v216
	v_sub_f32_e32 v48, v48, v216
	v_sub_f32_e32 v49, v49, v216
	v_sub_f32_e32 v114, v114, v216
	v_sub_f32_e32 v115, v115, v216
	v_sub_f32_e32 v116, v116, v216
	v_sub_f32_e32 v117, v117, v216
	v_sub_f32_e32 v118, v118, v216
	v_sub_f32_e32 v119, v119, v216
	v_sub_f32_e32 v120, v120, v216
	v_sub_f32_e32 v121, v121, v216
	v_sub_f32_e32 v122, v122, v216
	v_sub_f32_e32 v123, v123, v216
	v_sub_f32_e32 v124, v124, v216
	v_sub_f32_e32 v125, v125, v216
	v_sub_f32_e32 v126, v126, v216
	v_sub_f32_e32 v127, v127, v216
	v_sub_f32_e32 v128, v128, v216
	v_sub_f32_e32 v129, v129, v216
	v_mul_f32_e32 v213, v213, v217
	v_mul_f32_e32 v214, v214, v217
	v_mul_f32_e32 v178, v178, v217
	v_mul_f32_e32 v179, v179, v217
	v_mul_f32_e32 v2, v2, v217
	v_mul_f32_e32 v3, v3, v217
	v_mul_f32_e32 v4, v4, v217
	v_mul_f32_e32 v5, v5, v217
	v_mul_f32_e32 v6, v6, v217
	v_mul_f32_e32 v7, v7, v217
	v_mul_f32_e32 v8, v8, v217
	v_mul_f32_e32 v9, v9, v217
	v_mul_f32_e32 v10, v10, v217
	v_mul_f32_e32 v11, v11, v217
	v_mul_f32_e32 v12, v12, v217
	v_mul_f32_e32 v13, v13, v217
	v_mul_f32_e32 v14, v14, v217
	v_mul_f32_e32 v15, v15, v217
	v_mul_f32_e32 v16, v16, v217
	v_mul_f32_e32 v17, v17, v217
	v_mul_f32_e32 v18, v18, v217
	v_mul_f32_e32 v19, v19, v217
	v_mul_f32_e32 v20, v20, v217
	v_mul_f32_e32 v21, v21, v217
	v_mul_f32_e32 v22, v22, v217
	v_mul_f32_e32 v23, v23, v217
	v_mul_f32_e32 v24, v24, v217
	v_mul_f32_e32 v25, v25, v217
	v_mul_f32_e32 v26, v26, v217
	v_mul_f32_e32 v27, v27, v217
	v_mul_f32_e32 v28, v28, v217
	v_mul_f32_e32 v29, v29, v217
	v_mul_f32_e32 v30, v30, v217
	v_mul_f32_e32 v31, v31, v217
	v_mul_f32_e32 v32, v32, v217
	v_mul_f32_e32 v33, v33, v217
	v_cndmask_b32_e32 v220, v220, v228, vcc
	v_cndmask_b32_e64 v221, v221, -1, vcc
	s_andn2_b64 s[26:27], s[26:27], vcc

.Lna_sl_a_w1s:
	s_waitcnt lgkmcnt(0)
	s_cmp_eq_u64 s[42:43], 0
	s_cbranch_scc1 .Lna_sl_b_w1s
	ds_read_b128 v[146:149], v199 offset:0
	ds_read_b128 v[150:153], v199 offset:32
	ds_read_b128 v[154:157], v199 offset:64
	ds_read_b128 v[158:161], v199 offset:96
	s_waitcnt lgkmcnt(3)
	v_mfma_f32_32x32x16_bf16 v[34:49], v[146:149], v[98:101], v[114:129]
	s_waitcnt lgkmcnt(2)
	v_mfma_f32_32x32x16_bf16 v[34:49], v[150:153], v[102:105], v[34:49]
	s_waitcnt lgkmcnt(1)
	v_mfma_f32_32x32x16_bf16 v[34:49], v[154:157], v[106:109], v[34:49]
	s_waitcnt lgkmcnt(0)
	v_mfma_f32_32x32x16_bf16 v[34:49], v[158:161], v[110:113], v[34:49]
	v_add_u32_e32 v210, s25, v208
	ds_read_b128 v[146:149], v210 offset:0
	ds_read_b128 v[150:153], v210 offset:32
	ds_read_b128 v[154:157], v210 offset:64
	ds_read_b128 v[158:161], v210 offset:96
	s_waitcnt lgkmcnt(0)
	s_nop 15
	v_add_f32_e32 v34, v34, v146
	v_add_f32_e32 v35, v35, v147
	v_add_f32_e32 v36, v36, v148
	v_add_f32_e32 v37, v37, v149
	v_add_f32_e32 v38, v38, v150
	v_add_f32_e32 v39, v39, v151
	v_add_f32_e32 v40, v40, v152
	v_add_f32_e32 v41, v41, v153
	v_add_f32_e32 v42, v42, v154
	v_add_f32_e32 v43, v43, v155
	v_add_f32_e32 v44, v44, v156
	v_add_f32_e32 v45, v45, v157
	v_add_f32_e32 v46, v46, v158
	v_add_f32_e32 v47, v47, v159
	v_add_f32_e32 v48, v48, v160
	v_add_f32_e32 v49, v49, v161
	v_cndmask_b32_e64 v34, v229, v34, s[48:49]
	v_cndmask_b32_e64 v35, v229, v35, s[48:49]
	v_cndmask_b32_e64 v36, v229, v36, s[48:49]
	v_cndmask_b32_e64 v37, v229, v37, s[48:49]
	v_cndmask_b32_e64 v38, v229, v38, s[48:49]
	v_cndmask_b32_e64 v39, v229, v39, s[48:49]
	v_cndmask_b32_e64 v40, v229, v40, s[48:49]
	v_cndmask_b32_e64 v41, v229, v41, s[48:49]
	v_cndmask_b32_e64 v42, v229, v42, s[48:49]
	v_cndmask_b32_e64 v43, v229, v43, s[48:49]
	v_cndmask_b32_e64 v44, v229, v44, s[48:49]
	v_cndmask_b32_e64 v45, v229, v45, s[48:49]
	v_cndmask_b32_e64 v46, v229, v46, s[48:49]
	v_cndmask_b32_e64 v47, v229, v47, s[48:49]
	v_cndmask_b32_e64 v48, v229, v48, s[48:49]
	v_cndmask_b32_e64 v49, v229, v49, s[48:49]
	v_max3_f32 v216, v34, v35, v36
	v_max3_f32 v217, v42, v43, v44
	v_max3_f32 v216, v216, v37, v38
	v_max3_f32 v217, v217, v45, v46
	v_max3_f32 v216, v216, v39, v40
	v_max3_f32 v217, v217, v47, v48
	v_max_f32_e32 v216, v216, v41
	v_max_f32_e32 v217, v217, v49
	v_max_f32_e32 v216, v216, v217
	v_cmp_lt_f32_e32 vcc, 4.0, v216
	s_or_b64 vcc, vcc, s[26:27]
	s_cbranch_vccz .Lna_nr_w1s
	v_mov_b32_e32 v217, v216
	s_nop 1
	v_permlane32_swap_b32_e32 v216, v217
	v_max_f32_e32 v215, v216, v217
	s_nop 15
	v_max_f32_e32 v216, v215, v220
	v_cmp_lt_f32_e32 vcc, 0xf0c9f2ca, v215
	s_nop 1
	v_cndmask_b32_e32 v216, 0, v216, vcc
	v_exp_f32_e64 v217, -v216
	v_add_f32_e32 v212, v212, v216
	v_and_b32_e32 v217, v217, v221
	v_sub_f32_e32 v34, v34, v216
	v_sub_f32_e32 v35, v35, v216
	v_sub_f32_e32 v36, v36, v216
	v_sub_f32_e32 v37, v37, v216
	v_sub_f32_e32 v38, v38, v216
	v_sub_f32_e32 v39, v39, v216
	v_sub_f32_e32 v40, v40, v216
	v_sub_f32_e32 v41, v41, v216
	v_sub_f32_e32 v42, v42, v216
	v_sub_f32_e32 v43, v43, v216
	v_sub_f32_e32 v44, v44, v216
	v_sub_f32_e32 v45, v45, v216
	v_sub_f32_e32 v46, v46, v216
	v_sub_f32_e32 v47, v47, v216
	v_sub_f32_e32 v48, v48, v216
	v_sub_f32_e32 v49, v49, v216
	v_sub_f32_e32 v114, v114, v216
	v_sub_f32_e32 v115, v115, v216
	v_sub_f32_e32 v116, v116, v216
	v_sub_f32_e32 v117, v117, v216
	v_sub_f32_e32 v118, v118, v216
	v_sub_f32_e32 v119, v119, v216
	v_sub_f32_e32 v120, v120, v216
	v_sub_f32_e32 v121, v121, v216
	v_sub_f32_e32 v122, v122, v216
	v_sub_f32_e32 v123, v123, v216
	v_sub_f32_e32 v124, v124, v216
	v_sub_f32_e32 v125, v125, v216
	v_sub_f32_e32 v126, v126, v216
	v_sub_f32_e32 v127, v127, v216
	v_sub_f32_e32 v128, v128, v216
	v_sub_f32_e32 v129, v129, v216
	v_mul_f32_e32 v213, v213, v217
	v_mul_f32_e32 v214, v214, v217
	v_mul_f32_e32 v178, v178, v217
	v_mul_f32_e32 v179, v179, v217
	v_mul_f32_e32 v2, v2, v217
	v_mul_f32_e32 v3, v3, v217
	v_mul_f32_e32 v4, v4, v217
	v_mul_f32_e32 v5, v5, v217
	v_mul_f32_e32 v6, v6, v217
	v_mul_f32_e32 v7, v7, v217
	v_mul_f32_e32 v8, v8, v217
	v_mul_f32_e32 v9, v9, v217
	v_mul_f32_e32 v10, v10, v217
	v_mul_f32_e32 v11, v11, v217
	v_mul_f32_e32 v12, v12, v217
	v_mul_f32_e32 v13, v13, v217
	v_mul_f32_e32 v14, v14, v217
	v_mul_f32_e32 v15, v15, v217
	v_mul_f32_e32 v16, v16, v217
	v_mul_f32_e32 v17, v17, v217
	v_mul_f32_e32 v18, v18, v217
	v_mul_f32_e32 v19, v19, v217
	v_mul_f32_e32 v20, v20, v217
	v_mul_f32_e32 v21, v21, v217
	v_mul_f32_e32 v22, v22, v217
	v_mul_f32_e32 v23, v23, v217
	v_mul_f32_e32 v24, v24, v217
	v_mul_f32_e32 v25, v25, v217
	v_mul_f32_e32 v26, v26, v217
	v_mul_f32_e32 v27, v27, v217
	v_mul_f32_e32 v28, v28, v217
	v_mul_f32_e32 v29, v29, v217
	v_mul_f32_e32 v30, v30, v217
	v_mul_f32_e32 v31, v31, v217
	v_mul_f32_e32 v32, v32, v217
	v_mul_f32_e32 v33, v33, v217
	v_cndmask_b32_e32 v220, v220, v228, vcc
	v_cndmask_b32_e64 v221, v221, -1, vcc
	s_andn2_b64 s[26:27], s[26:27], vcc

.Lna_done_w1:
	s_add_i32 s24, s24, 1
	s_add_i32 s25, s25, 0x150
	s_sub_i32 s36, s24, s23
	s_cmp_lt_u32 s36, s63
	s_cselect_b64 s[40:41], -1, 0
	s_add_i32 s36, s36, 1
	s_cmp_lt_u32 s36, 8
	s_cselect_b64 s[44:45], -1, 0
	s_sub_i32 s37, s36, s62
	s_cmp_lt_u32 s37, 8
	s_cselect_b64 s[46:47], -1, 0
	s_and_b64 s[48:49], s[44:45], s[64:65]
	s_andn2_b64 s[38:39], s[46:47], s[64:65]
	s_or_b64 s[48:49], s[48:49], s[38:39]
	s_or_b64 s[42:43], s[44:45], s[46:47]
	s_and_b64 s[44:45], s[44:45], s[46:47]
	s_and_b64 s[44:45], s[44:45], s[40:41]
	s_cmp_eq_u64 s[44:45], 0
	s_cbranch_scc1 .Lna_slow_w0
	ds_read_b128 v[146:149], v199 offset:9216
	ds_read_b128 v[150:153], v199 offset:9248
	ds_read_b128 v[154:157], v199 offset:9280
	ds_read_b128 v[158:161], v199 offset:9312
	v_add_u32_e32 v210, s25, v208
	v_exp_f32_e32 v34, v34
	v_exp_f32_e32 v35, v35
	v_exp_f32_e32 v36, v36
	v_exp_f32_e32 v37, v37
	v_add_f32_e32 v213, v213, v34
	v_add_f32_e32 v214, v214, v35
	s_waitcnt lgkmcnt(3)
	v_mfma_f32_32x32x16_bf16 v[66:81], v[146:149], v[98:101], v[114:129]
	ds_read_b64 v[162:163], v201 offset:0
	ds_read_b64 v[164:165], v201 offset:16
	v_add_f32_e32 v178, v178, v36
	v_add_f32_e32 v179, v179, v37
	v_exp_f32_e32 v38, v38
	v_exp_f32_e32 v39, v39
	v_exp_f32_e32 v40, v40
	v_exp_f32_e32 v41, v41
	s_waitcnt lgkmcnt(4)
	v_mfma_f32_32x32x16_bf16 v[66:81], v[150:153], v[102:105], v[66:81]
	ds_read_b64 v[166:167], v201 offset:4352
	ds_read_b64 v[168:169], v201 offset:4368
	v_add_f32_e32 v213, v213, v38
	v_add_f32_e32 v214, v214, v39
	v_add_f32_e32 v178, v178, v40
	v_add_f32_e32 v179, v179, v41
	v_cvt_pk_bf16_f32 v34, v34, v35
	v_cvt_pk_bf16_f32 v35, v36, v37
	v_cvt_pk_bf16_f32 v36, v38, v39
	v_cvt_pk_bf16_f32 v37, v40, v41
	s_waitcnt lgkmcnt(5)
	v_mfma_f32_32x32x16_bf16 v[66:81], v[154:157], v[106:109], v[66:81]
	ds_read_b64 v[170:171], v201 offset:32
	ds_read_b64 v[172:173], v201 offset:48
	v_exp_f32_e32 v42, v42
	v_exp_f32_e32 v43, v43
	v_exp_f32_e32 v44, v44
	v_exp_f32_e32 v45, v45
	v_add_f32_e32 v213, v213, v42
	s_waitcnt lgkmcnt(6)
	v_mfma_f32_32x32x16_bf16 v[66:81], v[158:161], v[110:113], v[66:81]
	ds_read_b64 v[174:175], v201 offset:4384
	ds_read_b64 v[176:177], v201 offset:4400
	ds_read_b128 v[146:149], v210 offset:0
	ds_read_b128 v[150:153], v210 offset:32
	ds_read_b128 v[154:157], v210 offset:64
	ds_read_b128 v[158:161], v210 offset:96
	v_add_f32_e32 v214, v214, v43
	v_add_f32_e32 v178, v178, v44
	v_add_f32_e32 v179, v179, v45
	v_exp_f32_e32 v46, v46
	v_exp_f32_e32 v47, v47
	v_exp_f32_e32 v48, v48
	s_waitcnt lgkmcnt(10)
	v_mfma_f32_32x32x16_bf16 v[2:17], v[162:165], v[34:37], v[2:17]
	v_exp_f32_e32 v49, v49
	v_add_f32_e32 v213, v213, v46
	v_add_f32_e32 v214, v214, v47
	v_add_f32_e32 v178, v178, v48
	v_add_f32_e32 v179, v179, v49
	v_cvt_pk_bf16_f32 v42, v42, v43
	v_cvt_pk_bf16_f32 v43, v44, v45
	v_cvt_pk_bf16_f32 v44, v46, v47
	s_waitcnt lgkmcnt(8)
	v_mfma_f32_32x32x16_bf16 v[18:33], v[166:169], v[34:37], v[18:33]
	v_cvt_pk_bf16_f32 v45, v48, v49
	s_waitcnt lgkmcnt(0)
	v_add_f32_e32 v66, v66, v146
	v_add_f32_e32 v67, v67, v147
	v_add_f32_e32 v68, v68, v148
	v_add_f32_e32 v69, v69, v149
	v_add_f32_e32 v70, v70, v150
	v_add_f32_e32 v71, v71, v151
	v_add_f32_e32 v72, v72, v152
	v_add_f32_e32 v73, v73, v153
	v_mfma_f32_32x32x16_bf16 v[2:17], v[170:173], v[42:45], v[2:17]
	v_add_f32_e32 v74, v74, v154
	v_add_f32_e32 v75, v75, v155
	v_add_f32_e32 v76, v76, v156
	v_add_f32_e32 v77, v77, v157
	v_add_f32_e32 v78, v78, v158
	v_add_f32_e32 v79, v79, v159
	v_add_f32_e32 v80, v80, v160
	v_add_f32_e32 v81, v81, v161
	v_max3_f32 v216, v66, v67, v68
	v_mfma_f32_32x32x16_bf16 v[18:33], v[174:177], v[42:45], v[18:33]
	s_waitcnt vmcnt(2)
	ds_write_b128 v204, v[188:191] offset:0
	ds_write_b64 v205, v[192:193] offset:8704
	ds_write_b64 v205, v[194:195] offset:8712
	global_load_dwordx4 v[188:191], v206, s[12:13]
	s_add_i32 s20, s20, 1
	s_add_u32 s12, s12, 0x2000
	s_addc_u32 s13, s13, 0
	s_cmp_eq_u32 s20, s22
	s_cselect_b32 s12, s16, s12
	s_cselect_b32 s13, s17, s13
	global_load_dwordx4 v[192:195], v207, s[14:15]
	s_add_i32 s21, s21, 1
	s_add_u32 s14, s14, 0x80
	s_addc_u32 s15, s15, 0
	s_cmp_eq_u32 s21, s22
	s_cselect_b32 s14, s18, s14
	s_cselect_b32 s15, s19, s15
	v_max3_f32 v217, v74, v75, v76
	v_max3_f32 v216, v216, v69, v70
	v_max3_f32 v217, v217, v77, v78
	v_max3_f32 v216, v216, v71, v72
	v_max3_f32 v217, v217, v79, v80
	v_max_f32_e32 v216, v216, v73
	v_max_f32_e32 v217, v217, v81
	v_max_f32_e32 v216, v216, v217
	v_cmp_lt_f32_e32 vcc, 4.0, v216
	s_or_b64 vcc, vcc, s[26:27]
	s_cbranch_vccz .Lna_nr_w0f
	v_mov_b32_e32 v217, v216
	s_nop 1
	v_permlane32_swap_b32_e32 v216, v217
	v_max_f32_e32 v215, v216, v217
	s_nop 15
	v_max_f32_e32 v216, v215, v220
	v_cmp_lt_f32_e32 vcc, 0xf0c9f2ca, v215
	s_nop 1
	v_cndmask_b32_e32 v216, 0, v216, vcc
	v_exp_f32_e64 v217, -v216
	v_add_f32_e32 v212, v212, v216
	v_and_b32_e32 v217, v217, v221
	v_sub_f32_e32 v66, v66, v216
	v_sub_f32_e32 v67, v67, v216
	v_sub_f32_e32 v68, v68, v216
	v_sub_f32_e32 v69, v69, v216
	v_sub_f32_e32 v70, v70, v216
	v_sub_f32_e32 v71, v71, v216
	v_sub_f32_e32 v72, v72, v216
	v_sub_f32_e32 v73, v73, v216
	v_sub_f32_e32 v74, v74, v216
	v_sub_f32_e32 v75, v75, v216
	v_sub_f32_e32 v76, v76, v216
	v_sub_f32_e32 v77, v77, v216
	v_sub_f32_e32 v78, v78, v216
	v_sub_f32_e32 v79, v79, v216
	v_sub_f32_e32 v80, v80, v216
	v_sub_f32_e32 v81, v81, v216
	v_sub_f32_e32 v114, v114, v216
	v_sub_f32_e32 v115, v115, v216
	v_sub_f32_e32 v116, v116, v216
	v_sub_f32_e32 v117, v117, v216
	v_sub_f32_e32 v118, v118, v216
	v_sub_f32_e32 v119, v119, v216
	v_sub_f32_e32 v120, v120, v216
	v_sub_f32_e32 v121, v121, v216
	v_sub_f32_e32 v122, v122, v216
	v_sub_f32_e32 v123, v123, v216
	v_sub_f32_e32 v124, v124, v216
	v_sub_f32_e32 v125, v125, v216
	v_sub_f32_e32 v126, v126, v216
	v_sub_f32_e32 v127, v127, v216
	v_sub_f32_e32 v128, v128, v216
	v_sub_f32_e32 v129, v129, v216
	v_mul_f32_e32 v213, v213, v217
	v_mul_f32_e32 v214, v214, v217
	v_mul_f32_e32 v178, v178, v217
	v_mul_f32_e32 v179, v179, v217
	v_mul_f32_e32 v2, v2, v217
	v_mul_f32_e32 v3, v3, v217
	v_mul_f32_e32 v4, v4, v217
	v_mul_f32_e32 v5, v5, v217
	v_mul_f32_e32 v6, v6, v217
	v_mul_f32_e32 v7, v7, v217
	v_mul_f32_e32 v8, v8, v217
	v_mul_f32_e32 v9, v9, v217
	v_mul_f32_e32 v10, v10, v217
	v_mul_f32_e32 v11, v11, v217
	v_mul_f32_e32 v12, v12, v217
	v_mul_f32_e32 v13, v13, v217
	v_mul_f32_e32 v14, v14, v217
	v_mul_f32_e32 v15, v15, v217
	v_mul_f32_e32 v16, v16, v217
	v_mul_f32_e32 v17, v17, v217
	v_mul_f32_e32 v18, v18, v217
	v_mul_f32_e32 v19, v19, v217
	v_mul_f32_e32 v20, v20, v217
	v_mul_f32_e32 v21, v21, v217
	v_mul_f32_e32 v22, v22, v217
	v_mul_f32_e32 v23, v23, v217
	v_mul_f32_e32 v24, v24, v217
	v_mul_f32_e32 v25, v25, v217
	v_mul_f32_e32 v26, v26, v217
	v_mul_f32_e32 v27, v27, v217
	v_mul_f32_e32 v28, v28, v217
	v_mul_f32_e32 v29, v29, v217
	v_mul_f32_e32 v30, v30, v217
	v_mul_f32_e32 v31, v31, v217
	v_mul_f32_e32 v32, v32, v217
	v_mul_f32_e32 v33, v33, v217
	v_cndmask_b32_e32 v220, v220, v228, vcc
	v_cndmask_b32_e64 v221, v221, -1, vcc
	s_andn2_b64 s[26:27], s[26:27], vcc

.Lna_sl_a_w0s:
	s_waitcnt lgkmcnt(0)
	s_cmp_eq_u64 s[42:43], 0
	s_cbranch_scc1 .Lna_sl_b_w0s
	ds_read_b128 v[146:149], v199 offset:9216
	ds_read_b128 v[150:153], v199 offset:9248
	ds_read_b128 v[154:157], v199 offset:9280
	ds_read_b128 v[158:161], v199 offset:9312
	s_waitcnt lgkmcnt(3)
	v_mfma_f32_32x32x16_bf16 v[66:81], v[146:149], v[98:101], v[114:129]
	s_waitcnt lgkmcnt(2)
	v_mfma_f32_32x32x16_bf16 v[66:81], v[150:153], v[102:105], v[66:81]
	s_waitcnt lgkmcnt(1)
	v_mfma_f32_32x32x16_bf16 v[66:81], v[154:157], v[106:109], v[66:81]
	s_waitcnt lgkmcnt(0)
	v_mfma_f32_32x32x16_bf16 v[66:81], v[158:161], v[110:113], v[66:81]
	v_add_u32_e32 v210, s25, v208
	ds_read_b128 v[146:149], v210 offset:0
	ds_read_b128 v[150:153], v210 offset:32
	ds_read_b128 v[154:157], v210 offset:64
	ds_read_b128 v[158:161], v210 offset:96
	s_waitcnt lgkmcnt(0)
	s_nop 15
	v_add_f32_e32 v66, v66, v146
	v_add_f32_e32 v67, v67, v147
	v_add_f32_e32 v68, v68, v148
	v_add_f32_e32 v69, v69, v149
	v_add_f32_e32 v70, v70, v150
	v_add_f32_e32 v71, v71, v151
	v_add_f32_e32 v72, v72, v152
	v_add_f32_e32 v73, v73, v153
	v_add_f32_e32 v74, v74, v154
	v_add_f32_e32 v75, v75, v155
	v_add_f32_e32 v76, v76, v156
	v_add_f32_e32 v77, v77, v157
	v_add_f32_e32 v78, v78, v158
	v_add_f32_e32 v79, v79, v159
	v_add_f32_e32 v80, v80, v160
	v_add_f32_e32 v81, v81, v161
	v_cndmask_b32_e64 v66, v229, v66, s[48:49]
	v_cndmask_b32_e64 v67, v229, v67, s[48:49]
	v_cndmask_b32_e64 v68, v229, v68, s[48:49]
	v_cndmask_b32_e64 v69, v229, v69, s[48:49]
	v_cndmask_b32_e64 v70, v229, v70, s[48:49]
	v_cndmask_b32_e64 v71, v229, v71, s[48:49]
	v_cndmask_b32_e64 v72, v229, v72, s[48:49]
	v_cndmask_b32_e64 v73, v229, v73, s[48:49]
	v_cndmask_b32_e64 v74, v229, v74, s[48:49]
	v_cndmask_b32_e64 v75, v229, v75, s[48:49]
	v_cndmask_b32_e64 v76, v229, v76, s[48:49]
	v_cndmask_b32_e64 v77, v229, v77, s[48:49]
	v_cndmask_b32_e64 v78, v229, v78, s[48:49]
	v_cndmask_b32_e64 v79, v229, v79, s[48:49]
	v_cndmask_b32_e64 v80, v229, v80, s[48:49]
	v_cndmask_b32_e64 v81, v229, v81, s[48:49]
	v_max3_f32 v216, v66, v67, v68
	v_max3_f32 v217, v74, v75, v76
	v_max3_f32 v216, v216, v69, v70
	v_max3_f32 v217, v217, v77, v78
	v_max3_f32 v216, v216, v71, v72
	v_max3_f32 v217, v217, v79, v80
	v_max_f32_e32 v216, v216, v73
	v_max_f32_e32 v217, v217, v81
	v_max_f32_e32 v216, v216, v217
	v_cmp_lt_f32_e32 vcc, 4.0, v216
	s_or_b64 vcc, vcc, s[26:27]
	s_cbranch_vccz .Lna_nr_w0s
	v_mov_b32_e32 v217, v216
	s_nop 1
	v_permlane32_swap_b32_e32 v216, v217
	v_max_f32_e32 v215, v216, v217
	s_nop 15
	v_max_f32_e32 v216, v215, v220
	v_cmp_lt_f32_e32 vcc, 0xf0c9f2ca, v215
	s_nop 1
	v_cndmask_b32_e32 v216, 0, v216, vcc
	v_exp_f32_e64 v217, -v216
	v_add_f32_e32 v212, v212, v216
	v_and_b32_e32 v217, v217, v221
	v_sub_f32_e32 v66, v66, v216
	v_sub_f32_e32 v67, v67, v216
	v_sub_f32_e32 v68, v68, v216
	v_sub_f32_e32 v69, v69, v216
	v_sub_f32_e32 v70, v70, v216
	v_sub_f32_e32 v71, v71, v216
	v_sub_f32_e32 v72, v72, v216
	v_sub_f32_e32 v73, v73, v216
	v_sub_f32_e32 v74, v74, v216
	v_sub_f32_e32 v75, v75, v216
	v_sub_f32_e32 v76, v76, v216
	v_sub_f32_e32 v77, v77, v216
	v_sub_f32_e32 v78, v78, v216
	v_sub_f32_e32 v79, v79, v216
	v_sub_f32_e32 v80, v80, v216
	v_sub_f32_e32 v81, v81, v216
	v_sub_f32_e32 v114, v114, v216
	v_sub_f32_e32 v115, v115, v216
	v_sub_f32_e32 v116, v116, v216
	v_sub_f32_e32 v117, v117, v216
	v_sub_f32_e32 v118, v118, v216
	v_sub_f32_e32 v119, v119, v216
	v_sub_f32_e32 v120, v120, v216
	v_sub_f32_e32 v121, v121, v216
	v_sub_f32_e32 v122, v122, v216
	v_sub_f32_e32 v123, v123, v216
	v_sub_f32_e32 v124, v124, v216
	v_sub_f32_e32 v125, v125, v216
	v_sub_f32_e32 v126, v126, v216
	v_sub_f32_e32 v127, v127, v216
	v_sub_f32_e32 v128, v128, v216
	v_sub_f32_e32 v129, v129, v216
	v_mul_f32_e32 v213, v213, v217
	v_mul_f32_e32 v214, v214, v217
	v_mul_f32_e32 v178, v178, v217
	v_mul_f32_e32 v179, v179, v217
	v_mul_f32_e32 v2, v2, v217
	v_mul_f32_e32 v3, v3, v217
	v_mul_f32_e32 v4, v4, v217
	v_mul_f32_e32 v5, v5, v217
	v_mul_f32_e32 v6, v6, v217
	v_mul_f32_e32 v7, v7, v217
	v_mul_f32_e32 v8, v8, v217
	v_mul_f32_e32 v9, v9, v217
	v_mul_f32_e32 v10, v10, v217
	v_mul_f32_e32 v11, v11, v217
	v_mul_f32_e32 v12, v12, v217
	v_mul_f32_e32 v13, v13, v217
	v_mul_f32_e32 v14, v14, v217
	v_mul_f32_e32 v15, v15, v217
	v_mul_f32_e32 v16, v16, v217
	v_mul_f32_e32 v17, v17, v217
	v_mul_f32_e32 v18, v18, v217
	v_mul_f32_e32 v19, v19, v217
	v_mul_f32_e32 v20, v20, v217
	v_mul_f32_e32 v21, v21, v217
	v_mul_f32_e32 v22, v22, v217
	v_mul_f32_e32 v23, v23, v217
	v_mul_f32_e32 v24, v24, v217
	v_mul_f32_e32 v25, v25, v217
	v_mul_f32_e32 v26, v26, v217
	v_mul_f32_e32 v27, v27, v217
	v_mul_f32_e32 v28, v28, v217
	v_mul_f32_e32 v29, v29, v217
	v_mul_f32_e32 v30, v30, v217
	v_mul_f32_e32 v31, v31, v217
	v_mul_f32_e32 v32, v32, v217
	v_mul_f32_e32 v33, v33, v217
	v_cndmask_b32_e32 v220, v220, v228, vcc
	v_cndmask_b32_e64 v221, v221, -1, vcc
	s_andn2_b64 s[26:27], s[26:27], vcc
